# 4-way stagger of CU groups (0-3 x ~3us) at start of in-proj, FFN-in, FFN-out GEMM phases
# baseline (speedup 1.0000x reference)
; #define GAS __attribute__((address_space(1)))
; #define PH unsigned char* ws = KA->ws; int L = Lc; asm volatile("" : "+s"(ws), "+s"(L)); const unsigned char* wl = ws + WS_W + (size_t)L * W_LAYER; (void)wl
; __global__ void __launch_bounds__(512, 2) mega_fwd(Args a) {
;     ...
;     for (int Lc = 0; Lc < 2; ++Lc) {
;         {
;             PH;
;             run_gemm(lds, (const bf16_t*)(ws + WS_XB), (const bf16_t*)(wl + WO_IN), T_TOK, NIN, DM, FIn{(GAS bf16_t*)(ws + WS_HA), (GAS float*)(ws + WS_FL), (GAS float*)(ws + WS_IW), (const GAS float*)(ws + WS_TRIG)});
.LBB0_109:
	v_readlane_b32 s2, v252, 42
	s_nop 3
	s_bfe_u32 s2, s2, 0x20003
	s_cmp_eq_u32 s2, 0
	s_cbranch_scc1 .Lstag_P1
.Lstagl_P1:
	s_sleep 80
	s_sub_u32 s2, s2, 1
	s_cmp_lg_u32 s2, 0
	s_cbranch_scc1 .Lstagl_P1

; #define GAS __attribute__((address_space(1)))
; #define GSYNC() do { XcdBarrier xb_; xb_.bar = (unsigned*)(KA->ws + WS_CTL) + 2048; xb_.x = xb_xcc_id(); xb_.st = (volatile LAS unsigned*)(lds + LDS_SLOT + 16); xcd_barrier(xb_); } while (0)
; #define PH unsigned char* ws = KA->ws; int L = Lc; asm volatile("" : "+s"(ws), "+s"(L)); const unsigned char* wl = ws + WS_W + (size_t)L * W_LAYER; (void)wl
; __global__ void __launch_bounds__(512, 2) mega_fwd(Args a) {
;     ...
;         GSYNC();
;         {
;             PH;
;             run_gemm(lds, (const bf16_t*)(ws + WS_XB), (const bf16_t*)(wl + WO_FF1), T_TOK, NFF1, DM, FFf1{(GAS bf16_t*)(ws + WS_HFF), (GAS bf16_t*)(ws + WS_PG)});
.LBB0_1347:
	s_or_b64 exec, exec, s[0:1]
	s_waitcnt lgkmcnt(0)
	s_barrier
	v_readlane_b32 s2, v252, 42
	s_nop 3
	s_bfe_u32 s2, s2, 0x20003
	s_cmp_eq_u32 s2, 0
	s_cbranch_scc1 .Lstag_P7

; #define GAS __attribute__((address_space(1)))
;     __device__ __forceinline__ bool next(int i, pg8::Unit& o) const { if (i >= 3) return false; o.pm = pm + i * dpm; o.pn = pn + 4 * i; return true; }
;     __device__ __forceinline__ bool next(int i, pg8::Unit& o) const { if (i != 0) return false; o = u; return true; }
; #define GSYNC() do { XcdBarrier xb_; xb_.bar = (unsigned*)(KA->ws + WS_CTL) + 2048; xb_.x = xb_xcc_id(); xb_.st = (volatile LAS unsigned*)(lds + LDS_SLOT + 16); xcd_barrier(xb_); } while (0)
; #define PH unsigned char* ws = KA->ws; int L = Lc; asm volatile("" : "+s"(ws), "+s"(L)); const unsigned char* wl = ws + WS_W + (size_t)L * W_LAYER; (void)wl
;     __host__ __device__ __forceinline__ bool next(int i, Unit& u) const {
;         const long L = (long)i * G + c; if (L >= nwg) return false;
;         int wgid = (int)L; { const int q = nwg / NXCD, r = nwg % NXCD, xcd = wgid % NXCD, off = wgid / NXCD; wgid = (xcd < r ? xcd * (q + 1) : r * (q + 1) + (xcd - r) * q) + off; }
; __global__ void __launch_bounds__(512, 2) mega_fwd(Args a) {
;     ...
;         GSYNC();
;         {
;             PH;
;             run_gemm_ff2(lds, (const bf16_t*)(ws + WS_HFF), (const bf16_t*)(wl + WO_FF2), T_TOK, DM, HFP, EpiFf2{(const GAS bf16_t*)(ws + WS_XB), (GAS bf16_t*)(ws + WS_PG)});
.Lstag_P8:
	s_load_dwordx2 s[2:3], s[84:85], 0x88
	v_readlane_b32 s1, v252, 52
	s_movk_i32 s4, 0x400
	s_mov_b32 s5, 0x10000
	s_movk_i32 s0, 0x1100
	s_waitcnt lgkmcnt(0)
	s_ashr_i32 s6, s5, 31
	s_lshr_b32 s6, s6, 24
	s_add_i32 s5, s5, s6
	s_ashr_i32 s23, s5, 8
	s_ashr_i32 s5, s4, 31
	s_lshr_b32 s5, s5, 24
	s_add_i32 s4, s4, s5
	s_ashr_i32 s10, s4, 8
	s_mul_i32 s4, s10, s23
	v_mov_b32_e32 v14, v230
	v_readlane_b32 s6, v252, 6
	s_cmp_ge_i32 s6, s4
	v_readfirstlane_b32 s16, v14
	v_readlane_b32 s7, v252, 7
	s_cbranch_scc1 .LBB0_1527
	s_ashr_i32 s5, s4, 31
	s_lshr_b32 s6, s5, 29
	s_add_i32 s6, s4, s6
	s_ashr_i32 s44, s6, 3
	s_and_b32 s6, s6, -8
	s_sub_i32 s45, s4, s6
	s_add_i32 s46, s44, 1
	v_readlane_b32 s6, v252, 11
	s_cmp_ge_i32 s6, s45
	s_mov_b64 s[6:7], -1
	s_mul_i32 s47, s46, s45
	s_cbranch_scc0 .LBB0_1498
	v_readlane_b32 s6, v252, 11
	s_sub_i32 s6, s6, s45
	s_mul_i32 s6, s6, s44
	s_add_i32 s11, s6, s47
	s_mov_b64 s[6:7], 0
